# v38 + unit prologue init ahead of the first-tile wait/barrier in all three attention loops
# baseline (speedup 1.0000x reference)
; #define ATT_BAR() asm volatile("s_waitcnt lgkmcnt(0)\n\ts_barrier" ::: "memory")
; #define ATT_BAR() asm volatile("s_waitcnt vmcnt(0) lgkmcnt(0)\n\ts_barrier" ::: "memory")
; template <int DQK>
; __device__ __forceinline__ void attn_pass4(LAS unsigned char* lds, const bf16* Qp, int qpitch, const bf16* Kp, int kpitch, const bf16* Vp, int vpitch, int q0, f32x16 (&o)[4], float (&rl)[16]) {
;     ...
; #pragma unroll
;     for (int db = 0; db < 4; ++db)
; #pragma unroll
;         for (int r = 0; r < 16; ++r) o[db][r] = 0.f;
;     float mhat = 0.f, l = 0.f;
;     f32x16 negm;
; #pragma unroll
;     for (int r = 0; r < 16; ++r) negm[r] = 0.f;
;     ...
;     ATT_DMA(0, 0, 0); ATT_BAR();
.LBB0_2149:
	s_andn2_b32 s2, s2, 63
	s_lshl_b32 s2, s2, 2
	s_add_i32 s10, s66, 0x100
	s_add_i32 s3, s2, 0
	v_and_b32_e32 v179, 63, v0
	s_add_i32 s3, s3, 0x1b800
	s_lshr_b32 s69, s10, 6
	v_mul_u32_u24_e32 v3, 0x190, v2
	v_lshlrev_b32_e32 v4, 1, v0
	v_lshlrev_b32_e32 v5, 3, v0
	s_cmp_lt_i32 s67, 8
	s_mov_b64 s[56:57], -1
	v_cmp_gt_u32_e64 s[10:11], 32, v179
	v_add3_u32 v200, 0, v3, v178
	v_lshlrev_b32_e32 v201, 2, v195
	v_lshl_add_u32 v196, v2, 2, s3
	v_lshrrev_b32_e32 v202, 2, v0
	v_and_b32_e32 v198, 32, v4
	v_and_b32_e32 v199, 24, v5
	s_cbranch_scc0 .LBB0_2172
	v_and_or_b32 v0, v202, 3, v201
	v_mad_u32_u24 v0, v0, s30, 0
	v_mov_b32_e32 v14, v1
	v_mov_b32_e32 v15, v1
	s_lshl_b32 s2, s67, 10
	v_add3_u32 v203, v0, v198, v199
	v_mov_b32_e32 v0, v1
	v_mov_b32_e32 v2, v1
	v_mov_b32_e32 v3, v1
	v_mov_b32_e32 v4, v1
	v_mov_b32_e32 v5, v1
	v_mov_b32_e32 v6, v1
	v_mov_b32_e32 v7, v1
	v_mov_b32_e32 v8, v1
	v_mov_b32_e32 v9, v1
	v_mov_b32_e32 v10, v1
	v_mov_b32_e32 v11, v1
	v_mov_b32_e32 v12, v1
	v_mov_b32_e32 v13, v1
	v_mov_b32_e32 v204, 0
	v_mov_b64_e32 v[30:31], v[14:15]
	v_mov_b64_e32 v[46:47], v[14:15]
	v_mov_b64_e32 v[62:63], v[14:15]
	v_mov_b64_e32 v[78:79], v[14:15]
	s_add_i32 s24, s2, 0xc800
	s_or_b32 s25, s68, 31
	v_mov_b32_e32 v181, v1
	v_mov_b32_e32 v183, v1
	s_lshl_b32 s72, s70, 10
	v_mov_b32_e32 v185, v1
	s_lshl_b32 s73, s71, 10
	v_mov_b32_e32 v191, v1
	s_movk_i32 s74, 0x6000
	v_mov_b32_e32 v187, v1
	v_mov_b32_e32 v189, v1
	v_mov_b32_e32 v193, v1
	s_mov_b32 s78, 0
	s_mov_b32 s75, 63
	s_mov_b64 s[56:57], s[42:43]
	s_mov_b64 s[58:59], s[40:41]
	v_mov_b64_e32 v[28:29], v[12:13]
	v_mov_b64_e32 v[26:27], v[10:11]
	v_mov_b64_e32 v[24:25], v[8:9]
	v_mov_b64_e32 v[22:23], v[6:7]
	v_mov_b64_e32 v[20:21], v[4:5]
	v_mov_b64_e32 v[18:19], v[2:3]
	v_mov_b64_e32 v[16:17], v[0:1]
	v_mov_b64_e32 v[44:45], v[12:13]
	v_mov_b64_e32 v[42:43], v[10:11]
	v_mov_b64_e32 v[40:41], v[8:9]
	v_mov_b64_e32 v[38:39], v[6:7]
	v_mov_b64_e32 v[36:37], v[4:5]
	v_mov_b64_e32 v[34:35], v[2:3]
	v_mov_b64_e32 v[32:33], v[0:1]
	v_mov_b64_e32 v[60:61], v[12:13]
	v_mov_b64_e32 v[58:59], v[10:11]
	v_mov_b64_e32 v[56:57], v[8:9]
	v_mov_b64_e32 v[54:55], v[6:7]
	v_mov_b64_e32 v[52:53], v[4:5]
	v_mov_b64_e32 v[50:51], v[2:3]
	v_mov_b64_e32 v[48:49], v[0:1]
	v_mov_b64_e32 v[76:77], v[12:13]
	v_mov_b64_e32 v[74:75], v[10:11]
	v_mov_b64_e32 v[72:73], v[8:9]
	v_mov_b64_e32 v[70:71], v[6:7]
	v_mov_b64_e32 v[68:69], v[4:5]
	v_mov_b64_e32 v[66:67], v[2:3]
	v_mov_b64_e32 v[64:65], v[0:1]
	v_mov_b32_e32 v2, 0
	s_mov_b32 s60, 0
	v_mov_b32_e32 v80, 0
	v_mov_b32_e32 v81, v204
	v_mov_b32_e32 v82, v204
	v_mov_b32_e32 v83, v204
	v_mov_b32_e32 v84, v204
	v_mov_b32_e32 v85, v204
	v_mov_b32_e32 v86, v204
	v_mov_b32_e32 v87, v204
	v_mov_b32_e32 v88, v204
	v_mov_b32_e32 v89, v204
	v_mov_b32_e32 v90, v204
	v_mov_b32_e32 v91, v204
	v_mov_b32_e32 v92, v204
	v_mov_b32_e32 v93, v204
	v_mov_b32_e32 v94, v204
	v_mov_b32_e32 v95, v204
	s_waitcnt vmcnt(0) lgkmcnt(0)
	s_barrier
